# RET3 via LDS-DMA staging + attention K tile via LDS + lane-permuted (quad-row-contiguous) split-K epilogue stores in D1/WO/D2
# speedup vs baseline: 1.0782x; 1.0249x over previous
.LBB0_504:
	v_and_b32_e32 v254, 63, v128
	v_and_b32_e32 v255, 3, v254
	v_lshrrev_b32_e32 v254, 2, v254
	v_lshl_or_b32 v254, v255, 4, v254
	v_lshlrev_b32_e32 v254, 2, v254
	s_cmp_lt_i32 s69, 2
	s_mov_b32 s30, 0xff05000
	s_cselect_b32 s30, s30, 0x1aa05000
	s_add_u32 s30, s50, s30
	s_addc_u32 s31, s51, 0
	s_bitcmp1_b32 s69, 0
	s_cselect_b32 s52, 0x2400000, 0
	s_add_u32 s30, s30, s52
	v_lshl_or_b32 v152, s76, 8, v147
	v_lshl_add_u32 v154, s77, 8, v129
	s_addc_u32 s31, s31, 0
	v_ashrrev_i32_e32 v153, 31, v152
	v_ashrrev_i32_e32 v155, 31, v154
	v_lshl_add_u64 v[152:153], v[152:153], 1, s[30:31]
	v_lshlrev_b64 v[156:157], 12, v[154:155]
	v_lshl_add_u64 v[156:157], v[152:153], 0, v[156:157]
	s_mov_b64 s[30:31], 0x80000
	v_cvt_pk_bf16_f32 v68, v68, v69
	v_cvt_pk_bf16_f32 v69, v70, v71
	v_cvt_pk_bf16_f32 v70, v64, v65
	v_lshl_add_u64 v[64:65], v[156:157], 0, s[30:31]
	s_mov_b32 s30, 0x80000
	v_cvt_pk_bf16_f32 v60, v60, v61
	v_cvt_pk_bf16_f32 v61, v62, v63
	v_cvt_pk_bf16_f32 v62, v56, v57
	v_add_co_u32_e32 v56, vcc, s30, v156
	v_cvt_pk_bf16_f32 v44, v44, v45
	s_nop 0
	v_addc_co_u32_e32 v57, vcc, 0, v157, vcc
	v_cvt_pk_bf16_f32 v45, v46, v47
	v_cvt_pk_bf16_f32 v46, v40, v41
	v_cvt_pk_bf16_f32 v47, v42, v43
	ds_bpermute_b32 v238, v254, v44
	ds_bpermute_b32 v239, v254, v45
	ds_bpermute_b32 v240, v254, v46
	ds_bpermute_b32 v241, v254, v47
	ds_bpermute_b32 v236, v254, v64
	ds_bpermute_b32 v237, v254, v65
	s_mov_b64 s[30:31], 0x90000
	v_cvt_pk_bf16_f32 v108, v108, v109
	v_add_co_u32_e32 v46, vcc, s72, v156
	v_cvt_pk_bf16_f32 v109, v110, v111
	v_cvt_pk_bf16_f32 v110, v104, v105
	v_or_b32_e32 v104, 16, v154
	v_lshl_add_u64 v[44:45], v[156:157], 0, s[30:31]
	v_addc_co_u32_e32 v47, vcc, 0, v157, vcc
	v_cvt_pk_bf16_f32 v28, v28, v29
	v_cvt_pk_bf16_f32 v29, v30, v31
	v_cvt_pk_bf16_f32 v30, v24, v25
	v_cvt_pk_bf16_f32 v31, v26, v27
	v_ashrrev_i32_e32 v105, 31, v104
	v_cvt_pk_bf16_f32 v92, v92, v93
	v_cvt_pk_bf16_f32 v93, v94, v95
	v_cvt_pk_bf16_f32 v94, v88, v89
	v_or_b32_e32 v88, 32, v154
	ds_bpermute_b32 v244, v254, v28
	ds_bpermute_b32 v245, v254, v29
	ds_bpermute_b32 v246, v254, v30
	ds_bpermute_b32 v247, v254, v31
	ds_bpermute_b32 v242, v254, v44
	ds_bpermute_b32 v243, v254, v45
	v_cvt_pk_bf16_f32 v111, v106, v107
	v_lshlrev_b64 v[104:105], 12, v[104:105]
	v_add_co_u32_e32 v30, vcc, s73, v156
	v_ashrrev_i32_e32 v89, 31, v88
	v_cvt_pk_bf16_f32 v76, v76, v77
	v_cvt_pk_bf16_f32 v77, v78, v79
	v_cvt_pk_bf16_f32 v78, v72, v73
	v_or_b32_e32 v72, 48, v154
	v_lshl_add_u64 v[28:29], v[156:157], 0, s[14:15]
	v_addc_co_u32_e32 v31, vcc, 0, v157, vcc
	v_cvt_pk_bf16_f32 v12, v12, v13
	v_cvt_pk_bf16_f32 v13, v14, v15
	v_cvt_pk_bf16_f32 v14, v8, v9
	v_cvt_pk_bf16_f32 v15, v10, v11
	ds_bpermute_b32 v250, v254, v108
	ds_bpermute_b32 v251, v254, v109
	ds_bpermute_b32 v252, v254, v110
	ds_bpermute_b32 v253, v254, v111
	ds_bpermute_b32 v248, v254, v156
	ds_bpermute_b32 v249, v254, v157
	v_cvt_pk_bf16_f32 v95, v90, v91
	v_lshlrev_b64 v[88:89], 12, v[88:89]
	v_lshl_add_u64 v[108:109], v[152:153], 0, v[104:105]
	v_ashrrev_i32_e32 v73, 31, v72
	s_waitcnt lgkmcnt(12)
	global_store_dwordx4 v[236:237], v[238:241], off offset:256
	s_nop 0
	ds_bpermute_b32 v238, v254, v12
	ds_bpermute_b32 v239, v254, v13
	ds_bpermute_b32 v240, v254, v14
	ds_bpermute_b32 v241, v254, v15
	ds_bpermute_b32 v236, v254, v28
	ds_bpermute_b32 v237, v254, v29
	s_waitcnt lgkmcnt(12)
	global_store_dwordx4 v[242:243], v[244:247], off offset:256
	s_nop 0
	ds_bpermute_b32 v244, v254, v92
	ds_bpermute_b32 v245, v254, v93
	ds_bpermute_b32 v246, v254, v94
	ds_bpermute_b32 v247, v254, v95
	ds_bpermute_b32 v242, v254, v108
	ds_bpermute_b32 v243, v254, v109
	v_cvt_pk_bf16_f32 v79, v74, v75
	v_add_co_u32_e32 v14, vcc, s74, v156
	v_lshl_add_u64 v[92:93], v[152:153], 0, v[88:89]
	v_lshlrev_b64 v[72:73], 12, v[72:73]
	v_addc_co_u32_e32 v15, vcc, 0, v157, vcc
	v_cvt_pk_bf16_f32 v124, v124, v125
	v_cvt_pk_bf16_f32 v125, v126, v127
	v_cvt_pk_bf16_f32 v126, v120, v121
	v_cvt_pk_bf16_f32 v127, v122, v123
	v_cvt_pk_bf16_f32 v104, v116, v117
	v_cvt_pk_bf16_f32 v105, v118, v119
	v_cvt_pk_bf16_f32 v106, v112, v113
	v_cvt_pk_bf16_f32 v107, v114, v115
	v_cvt_pk_bf16_f32 v88, v100, v101
	v_cvt_pk_bf16_f32 v89, v102, v103
	v_cvt_pk_bf16_f32 v90, v96, v97
	v_cvt_pk_bf16_f32 v91, v98, v99
	s_waitcnt lgkmcnt(12)
	global_store_dwordx4 v[248:249], v[250:253], off offset:256
	s_nop 0
	ds_bpermute_b32 v250, v254, v76
	ds_bpermute_b32 v251, v254, v77
	ds_bpermute_b32 v252, v254, v78
	ds_bpermute_b32 v253, v254, v79
	ds_bpermute_b32 v248, v254, v92
	ds_bpermute_b32 v249, v254, v93
	v_cvt_pk_bf16_f32 v74, v80, v81
	v_cvt_pk_bf16_f32 v75, v82, v83
	v_lshl_add_u64 v[76:77], v[152:153], 0, v[72:73]
	v_cvt_pk_bf16_f32 v72, v84, v85
	v_cvt_pk_bf16_f32 v73, v86, v87
	v_cvt_pk_bf16_f32 v71, v66, v67
	v_cvt_pk_bf16_f32 v63, v58, v59
	v_cvt_pk_bf16_f32 v40, v52, v53
	v_cvt_pk_bf16_f32 v41, v54, v55
	v_cvt_pk_bf16_f32 v42, v48, v49
	v_cvt_pk_bf16_f32 v43, v50, v51
	v_cvt_pk_bf16_f32 v24, v36, v37
	v_cvt_pk_bf16_f32 v25, v38, v39
	v_cvt_pk_bf16_f32 v26, v32, v33
	v_cvt_pk_bf16_f32 v27, v34, v35
	v_lshl_add_u64 v[12:13], v[156:157], 0, s[26:27]
	v_cvt_pk_bf16_f32 v8, v20, v21
	v_cvt_pk_bf16_f32 v9, v22, v23
	v_cvt_pk_bf16_f32 v10, v16, v17
	v_cvt_pk_bf16_f32 v11, v18, v19
	v_cvt_pk_bf16_f32 v4, v4, v5
	v_cvt_pk_bf16_f32 v5, v6, v7
	v_cvt_pk_bf16_f32 v6, v0, v1
	v_cvt_pk_bf16_f32 v7, v2, v3
	s_and_b64 vcc, exec, s[4:5]
	s_mov_b64 s[4:5], -1
	s_waitcnt lgkmcnt(12)
	global_store_dwordx4 v[236:237], v[238:241], off offset:256
	s_nop 0
	ds_bpermute_b32 v238, v254, v124
	ds_bpermute_b32 v239, v254, v125
	ds_bpermute_b32 v240, v254, v126
	ds_bpermute_b32 v241, v254, v127
	ds_bpermute_b32 v236, v254, v156
	ds_bpermute_b32 v237, v254, v157
	s_waitcnt lgkmcnt(12)
	global_store_dwordx4 v[242:243], v[244:247], off offset:256
	s_nop 0
	ds_bpermute_b32 v244, v254, v104
	ds_bpermute_b32 v245, v254, v105
	ds_bpermute_b32 v246, v254, v106
	ds_bpermute_b32 v247, v254, v107
	ds_bpermute_b32 v242, v254, v108
	ds_bpermute_b32 v243, v254, v109
	s_waitcnt lgkmcnt(12)
	global_store_dwordx4 v[248:249], v[250:253], off offset:256
	s_nop 0
	ds_bpermute_b32 v250, v254, v88
	ds_bpermute_b32 v251, v254, v89
	ds_bpermute_b32 v252, v254, v90
	ds_bpermute_b32 v253, v254, v91
	ds_bpermute_b32 v248, v254, v92
	ds_bpermute_b32 v249, v254, v93
	s_waitcnt lgkmcnt(12)
	global_store_dwordx4 v[236:237], v[238:241], off
	s_nop 0
	ds_bpermute_b32 v238, v254, v72
	ds_bpermute_b32 v239, v254, v73
	ds_bpermute_b32 v240, v254, v74
	ds_bpermute_b32 v241, v254, v75
	ds_bpermute_b32 v236, v254, v76
	ds_bpermute_b32 v237, v254, v77
	s_waitcnt lgkmcnt(12)
	global_store_dwordx4 v[242:243], v[244:247], off
	s_nop 0
	ds_bpermute_b32 v244, v254, v68
	ds_bpermute_b32 v245, v254, v69
	ds_bpermute_b32 v246, v254, v70
	ds_bpermute_b32 v247, v254, v71
	ds_bpermute_b32 v242, v254, v76
	ds_bpermute_b32 v243, v254, v77
	s_waitcnt lgkmcnt(12)
	global_store_dwordx4 v[248:249], v[250:253], off
	s_nop 0
	ds_bpermute_b32 v250, v254, v60
	ds_bpermute_b32 v251, v254, v61
	ds_bpermute_b32 v252, v254, v62
	ds_bpermute_b32 v253, v254, v63
	ds_bpermute_b32 v248, v254, v56
	ds_bpermute_b32 v249, v254, v57
	s_waitcnt lgkmcnt(12)
	global_store_dwordx4 v[236:237], v[238:241], off
	s_nop 0
	ds_bpermute_b32 v238, v254, v40
	ds_bpermute_b32 v239, v254, v41
	ds_bpermute_b32 v240, v254, v42
	ds_bpermute_b32 v241, v254, v43
	ds_bpermute_b32 v236, v254, v46
	ds_bpermute_b32 v237, v254, v47
	s_waitcnt lgkmcnt(12)
	global_store_dwordx4 v[242:243], v[244:247], off offset:256
	s_nop 0
	ds_bpermute_b32 v244, v254, v24
	ds_bpermute_b32 v245, v254, v25
	ds_bpermute_b32 v246, v254, v26
	ds_bpermute_b32 v247, v254, v27
	ds_bpermute_b32 v242, v254, v30
	ds_bpermute_b32 v243, v254, v31
	s_waitcnt lgkmcnt(12)
	global_store_dwordx4 v[248:249], v[250:253], off
	s_nop 0
	ds_bpermute_b32 v250, v254, v8
	ds_bpermute_b32 v251, v254, v9
	ds_bpermute_b32 v252, v254, v10
	ds_bpermute_b32 v253, v254, v11
	ds_bpermute_b32 v248, v254, v14
	ds_bpermute_b32 v249, v254, v15
	s_waitcnt lgkmcnt(12)
	global_store_dwordx4 v[236:237], v[238:241], off
	s_nop 0
	ds_bpermute_b32 v238, v254, v4
	ds_bpermute_b32 v239, v254, v5
	ds_bpermute_b32 v240, v254, v6
	ds_bpermute_b32 v241, v254, v7
	ds_bpermute_b32 v236, v254, v12
	ds_bpermute_b32 v237, v254, v13
	s_waitcnt lgkmcnt(12)
	global_store_dwordx4 v[242:243], v[244:247], off
	s_waitcnt lgkmcnt(6)
	global_store_dwordx4 v[248:249], v[250:253], off
	s_waitcnt lgkmcnt(0)
	global_store_dwordx4 v[236:237], v[238:241], off offset:256
	s_cbranch_vccnz .LBB0_493
	s_andn2_b64 vcc, exec, s[8:9]
	s_cbranch_vccnz .LBB0_492
	s_barrier
	s_branch .LBB0_492

.LBB0_974:
	s_cmpk_gt_i32 s34, 0xff
	v_lshrrev_b32_e32 v96, 7, v128
	s_cbranch_scc1 .LBB0_987
	v_lshrrev_b32_e32 v9, 3, v128
	v_lshlrev_b32_e32 v10, 3, v128
	v_mul_u32_u24_e32 v9, 0x250, v9
	v_and_b32_e32 v10, 56, v10
	v_add3_u32 v74, 0, v9, v10
	v_mbcnt_lo_u32_b32 v9, -1, 0
	v_mbcnt_hi_u32_b32 v9, -1, v9
	v_and_b32_e32 v12, 64, v9
	v_xor_b32_e32 v11, 16, v9
	v_add_u32_e32 v12, 64, v12
	v_cmp_lt_i32_e32 vcc, v11, v12
	v_mov_b32_e32 v45, 0
	v_bfe_u32 v8, v128, 4, 2
	v_cndmask_b32_e32 v11, v9, v11, vcc
	v_lshlrev_b32_e32 v76, 2, v11
	v_xor_b32_e32 v11, 32, v9
	v_cmp_lt_i32_e32 vcc, v11, v12
	s_add_u32 s6, s50, 0x14705000
	v_lshlrev_b32_e32 v44, 3, v8
	v_cndmask_b32_e32 v9, v9, v11, vcc
	v_lshlrev_b32_e32 v10, 2, v8
	v_lshlrev_b32_e32 v77, 2, v9
	s_addc_u32 s7, s51, 0
	v_lshlrev_b32_e32 v8, 4, v8
	v_mov_b32_e32 v9, v45
	v_lshrrev_b32_e32 v1, 6, v128
	v_lshl_add_u64 v[46:47], s[6:7], 0, v[8:9]
	v_lshl_add_u64 v[8:9], s[50:51], 0, v[44:45]
	s_mov_b64 s[10:11], 0x21605000
	s_waitcnt vmcnt(0)
	v_and_b32_e32 v2, 12, v1
	v_lshl_add_u64 v[48:49], v[8:9], 0, s[10:11]
	v_lshlrev_b32_e32 v8, 1, v128
	v_and_b32_e32 v65, 0xff, v128
	v_lshlrev_b32_e32 v0, 3, v2
	v_or_b32_e32 v1, 3, v1
	v_and_b32_e32 v7, 15, v128
	s_movk_i32 s8, 0x250
	v_and_b32_e32 v8, 0x80, v8
	s_movk_i32 s4, 0x7f
	v_lshl_add_u32 v3, v65, 1, 0
	v_mul_u32_u24_e32 v5, 0x1280, v2
	v_or_b32_e32 v2, 8, v0
	v_or_b32_e32 v4, 16, v0
	v_lshlrev_b32_e32 v6, 3, v1
	v_mul_u32_u24_e32 v1, 0x1280, v1
	v_and_b32_e32 v75, 64, v128
	v_mad_u32_u24 v7, v7, s8, v8
	s_movk_i32 s8, 0xff6f
	v_cmp_lt_u32_e64 s[4:5], s4, v65
	s_mov_b32 s9, 0
	v_add3_u32 v78, v7, v44, 0
	v_or_b32_e32 v79, v10, v75
	v_bitop3_b32 v80, v10, s8, v75 bitop3:0x36
	v_bitop3_b32 v81, v128, 15, 64 bitop3:0xe0
	s_lshl_b32 s14, s34, 5
	s_lshl_b32 s15, s94, 5
	s_movk_i32 s16, 0x5c00
	v_mov_b64_e32 v[50:51], s[6:7]
	v_lshlrev_b32_e32 v52, 1, v0
	v_add_u32_e32 v82, v3, v5
	v_lshlrev_b32_e32 v54, 1, v2
	v_lshlrev_b32_e32 v56, 1, v4
	v_lshlrev_b32_e32 v58, 1, v6
	v_add_u32_e32 v83, v3, v1
	s_mov_b32 s17, 0xc2fc0000
	s_movk_i32 s18, 0x60
	s_movk_i32 s19, 0x81
	s_movk_i32 s26, 0x6f
	s_movk_i32 s27, 0x50
	s_movk_i32 s28, 0x4f
	v_mov_b32_e32 v88, v45
	v_mov_b32_e32 v89, v45
	v_mov_b32_e32 v84, 0x42800000
	v_not_b32_e32 v85, 63
	v_mov_b32_e32 v60, 0x3e000000
	v_mov_b32_e32 v86, 0xff800000
	s_mov_b32 s29, s34
	v_and_b32_e32 v136, 63, v128
	v_lshrrev_b32_e32 v137, 3, v136
	v_and_b32_e32 v138, 7, v136
	v_readfirstlane_b32 s75, v128
	s_lshr_b32 s75, s75, 6
	s_and_b32 s76, s75, 1
	s_lshl_b32 s76, s76, 2
	v_lshrrev_b32_e32 v139, 1, v137
	v_add_u32_e32 v139, s76, v139
	v_and_b32_e32 v139, 7, v139
	v_xor_b32_e32 v138, v138, v139
	v_lshlrev_b32_e32 v138, 4, v138
	s_movk_i32 s77, 0x5c00
	v_mul_u32_u24_e32 v137, s77, v137
	v_add_u32_e32 v130, v137, v138
	v_mov_b32_e32 v131, 0
	v_and_b32_e32 v136, 15, v128
	v_bfe_u32 v137, v128, 4, 2
	v_lshrrev_b32_e32 v138, 1, v136
	v_lshlrev_b32_e32 v136, 7, v136
	s_lshl_b32 s76, s76, 11
	s_add_u32 s76, s76, 0xa000
	v_add_u32_e32 v136, s76, v136
	v_xor_b32_e32 v139, v137, v138
	v_lshl_add_u32 v132, v139, 4, v136
	v_add_u32_e32 v137, 4, v137
	v_xor_b32_e32 v139, v137, v138
	v_lshl_add_u32 v133, v139, 4, v136
	s_add_u32 s68, s50, 0x14705000
	s_addc_u32 s69, s51, 0
.LBB0_976:
	s_bfe_u32 s30, s29, 0x50002
	s_lshl_b32 s6, s29, 5
	s_and_b32 s6, s6, 0xfffff000
	s_lshl_b32 s7, s30, 7
	s_or_b32 s31, s7, s6
	s_and_b32 s35, s29, 3
	s_add_i32 s8, s31, 0xffffff80
	s_cmp_lg_u32 s30, 0
	v_add_u32_e32 v0, s8, v65
	s_cselect_b64 s[10:11], -1, 0
	v_mad_i64_i32 v[0:1], s[12:13], v0, s16, v[50:51]
	s_lshl_b32 s8, s35, 7
	s_or_b64 s[6:7], s[10:11], s[4:5]
	v_lshl_add_u64 v[6:7], v[0:1], 0, s[8:9]
	s_add_i32 s70, s31, 0xffffff80
	s_mul_hi_i32 s73, s70, 0x5c00
	s_mul_i32 s72, s70, 0x5c00
	s_add_u32 s72, s72, s68
	s_addc_u32 s73, s73, s69
	s_lshl_b32 s74, s35, 7
	s_add_u32 s74, s74, 0x800
	s_mul_i32 s78, s75, 0x2e000
	s_add_u32 s74, s74, s78
	s_add_u32 s72, s72, s74
	s_addc_u32 s73, s73, 0
	s_lshl_b32 s78, s75, 10
	s_add_u32 s78, s78, 0xa000
	s_mov_b32 m0, s78
	v_lshl_add_u64 v[136:137], s[72:73], 0, v[130:131]
	global_load_lds_dwordx4 v[136:137], off
	s_add_u32 s72, s72, 0x170000
	s_addc_u32 s73, s73, 0
	s_add_u32 s78, s78, 0x2000
	s_mov_b32 m0, s78
	v_lshl_add_u64 v[136:137], s[72:73], 0, v[130:131]
	global_load_lds_dwordx4 v[136:137], off
	s_add_u32 s72, s72, 0x170000
	s_addc_u32 s73, s73, 0
	s_add_u32 s78, s78, 0x2000
	s_mov_b32 m0, s78
	v_lshl_add_u64 v[136:137], s[72:73], 0, v[130:131]
	global_load_lds_dwordx4 v[136:137], off
	s_add_u32 s72, s72, 0x170000
	s_addc_u32 s73, s73, 0
	s_add_u32 s78, s78, 0x2000
	s_mov_b32 m0, s78
	v_lshl_add_u64 v[136:137], s[72:73], 0, v[130:131]
	global_load_lds_dwordx4 v[136:137], off
	v_mov_b32_e32 v0, 0
	v_mov_b32_e32 v1, 0
	v_mov_b32_e32 v2, 0
	v_mov_b32_e32 v3, 0
	s_and_saveexec_b64 s[12:13], s[6:7]
	s_cbranch_execz .LBB0_978
	v_mov_b32_e32 v53, v45
	v_lshl_add_u64 v[0:1], v[6:7], 0, v[52:53]
	global_load_dwordx4 v[0:3], v[0:1], off offset:2560

.LBB0_985:
	s_lshl_b32 s79, s33, 7
	v_add_u32_e32 v134, s79, v132
	v_add_u32_e32 v135, s79, v133
	v_add_u32_e32 v72, s33, v55
	v_mad_i64_i32 v[0:1], s[6:7], v72, s16, v[66:67]
	global_load_dwordx4 v[32:35], v[0:1], off
	global_load_dwordx4 v[40:43], v[0:1], off offset:64
	v_add_u32_e32 v0, 0xffffff80, v72
	v_max_i32_e32 v0, 0, v0
	v_mad_u64_u32 v[4:5], s[6:7], v0, s16, v[70:71]
	ds_read_b128 v[0:3], v134 offset:0
	s_nop 0
	ds_read_b128 v[4:7], v135 offset:0
	v_add_u32_e32 v59, s33, v75
	v_add_u32_e32 v61, 16, v72
	v_cmp_lt_u32_e32 vcc, s18, v59
	v_mov_b32_e32 v62, s31
	v_ashrrev_i32_e32 v73, 31, v72
	v_cndmask_b32_e32 v61, v61, v62, vcc
	v_max_i32_e32 v61, 0, v61
	v_mad_u64_u32 v[94:95], s[6:7], v61, s16, v[70:71]
	s_waitcnt vmcnt(0) lgkmcnt(1)
	v_mfma_f32_16x16x32_bf16 v[0:3], v[0:3], v[32:35], 0
	s_waitcnt lgkmcnt(0)
	v_mfma_f32_16x16x32_bf16 v[36:39], v[4:7], v[40:43], v[0:3]
	s_nop 5
	v_add_u32_e32 v0, 0xffffff90, v72
	v_max_i32_e32 v0, 0, v0
	v_mad_u64_u32 v[4:5], s[6:7], v0, s16, v[70:71]
	ds_read_b128 v[0:3], v134 offset:2048
	s_nop 0
	ds_read_b128 v[4:7], v135 offset:2048
	v_mov_b32_e32 v62, v36
	s_waitcnt lgkmcnt(1)
	v_mfma_f32_16x16x32_bf16 v[0:3], v[0:3], v[32:35], 0
	s_waitcnt lgkmcnt(0)
	v_mfma_f32_16x16x32_bf16 v[28:31], v[4:7], v[40:43], v[0:3]
	s_nop 5
	v_add_u32_e32 v0, 0xffffffa0, v72
	v_max_i32_e32 v0, 0, v0
	v_mad_u64_u32 v[4:5], s[6:7], v0, s16, v[70:71]
	ds_read_b128 v[0:3], v134 offset:4096
	s_nop 0
	ds_read_b128 v[4:7], v135 offset:4096
	s_waitcnt lgkmcnt(1)
	v_mfma_f32_16x16x32_bf16 v[0:3], v[0:3], v[32:35], 0
	s_waitcnt lgkmcnt(0)
	v_mfma_f32_16x16x32_bf16 v[24:27], v[4:7], v[40:43], v[0:3]
	s_nop 5
	v_add_u32_e32 v0, 0xffffffb0, v72
	v_max_i32_e32 v0, 0, v0
	v_mad_u64_u32 v[4:5], s[6:7], v0, s16, v[70:71]
	ds_read_b128 v[0:3], v134 offset:6144
	s_nop 0
	ds_read_b128 v[4:7], v135 offset:6144
	s_waitcnt lgkmcnt(1)
	v_mfma_f32_16x16x32_bf16 v[0:3], v[0:3], v[32:35], 0
	s_waitcnt lgkmcnt(0)
	v_mfma_f32_16x16x32_bf16 v[20:23], v[4:7], v[40:43], v[0:3]
	s_nop 5
	v_subrev_u32_e32 v0, 64, v72
	v_max_i32_e32 v0, 0, v0
	v_mad_u64_u32 v[4:5], s[6:7], v0, s16, v[70:71]
	ds_read_b128 v[0:3], v134 offset:8192
	s_nop 0
	ds_read_b128 v[4:7], v135 offset:8192
	s_waitcnt lgkmcnt(1)
	v_mfma_f32_16x16x32_bf16 v[0:3], v[0:3], v[32:35], 0
	s_waitcnt lgkmcnt(0)
	v_mfma_f32_16x16x32_bf16 v[16:19], v[4:7], v[40:43], v[0:3]
	s_nop 5
	v_subrev_u32_e32 v0, 48, v72
	v_max_i32_e32 v0, 0, v0
	v_mad_u64_u32 v[4:5], s[6:7], v0, s16, v[70:71]
	ds_read_b128 v[0:3], v134 offset:10240
	s_nop 0
	ds_read_b128 v[4:7], v135 offset:10240
	s_waitcnt lgkmcnt(1)
	v_mfma_f32_16x16x32_bf16 v[0:3], v[0:3], v[32:35], 0
	s_waitcnt lgkmcnt(0)
	v_mfma_f32_16x16x32_bf16 v[12:15], v[4:7], v[40:43], v[0:3]
	s_nop 5
	v_subrev_u32_e32 v0, 32, v72
	v_max_i32_e32 v0, 0, v0
	v_mad_u64_u32 v[4:5], s[6:7], v0, s16, v[70:71]
	ds_read_b128 v[0:3], v134 offset:12288
	s_nop 0
	ds_read_b128 v[4:7], v135 offset:12288
	s_waitcnt lgkmcnt(1)
	v_mfma_f32_16x16x32_bf16 v[0:3], v[0:3], v[32:35], 0
	s_waitcnt lgkmcnt(0)
	v_mfma_f32_16x16x32_bf16 v[8:11], v[4:7], v[40:43], v[0:3]
	s_nop 5
	v_add_u32_e32 v0, -16, v72
	v_max_i32_e32 v0, 0, v0
	v_mad_u64_u32 v[4:5], s[6:7], v0, s16, v[70:71]
	ds_read_b128 v[0:3], v134 offset:14336
	s_nop 0
	ds_read_b128 v[4:7], v135 offset:14336
	s_waitcnt lgkmcnt(1)
	v_mfma_f32_16x16x32_bf16 v[0:3], v[0:3], v[32:35], 0
	s_waitcnt lgkmcnt(0)
	v_mfma_f32_16x16x32_bf16 v[4:7], v[4:7], v[40:43], v[0:3]
	s_nop 5
	v_max_i32_e32 v0, 0, v72
	v_mad_u64_u32 v[90:91], s[6:7], v0, s16, v[70:71]
	ds_read_b128 v[0:3], v134 offset:16384
	s_nop 0
	ds_read_b128 v[90:93], v135 offset:16384
	v_cmp_lt_u32_e64 s[6:7], s26, v59
	s_or_b64 s[6:7], s[10:11], s[6:7]
	s_waitcnt lgkmcnt(1)
	v_mfma_f32_16x16x32_bf16 v[0:3], v[0:3], v[32:35], 0
	s_waitcnt lgkmcnt(0)
	v_mfma_f32_16x16x32_bf16 v[0:3], v[90:93], v[40:43], v[0:3]
	ds_read_b128 v[90:93], v134 offset:18432
	ds_read_b128 v[98:101], v135 offset:18432
	ds_read2_b64 v[106:109], v57 offset0:8 offset1:12
	s_waitcnt lgkmcnt(2)
	v_mfma_f32_16x16x32_bf16 v[32:35], v[90:93], v[32:35], 0
	s_waitcnt lgkmcnt(1)
	v_mfma_f32_16x16x32_bf16 v[32:35], v[98:101], v[40:43], v[32:35]
	v_add_u32_e32 v40, s33, v81
	v_add_u32_e32 v42, 0x80, v40
	v_add_u32_e32 v40, s33, v79
	v_sub_u32_e32 v43, v42, v40
	v_cvt_f32_i32_e32 v61, v43
	v_cmp_gt_u32_e32 vcc, s19, v43
	s_and_b64 vcc, s[10:11], vcc
	s_add_i32 s33, s33, 16
	v_pk_mul_f32 v[40:41], v[62:63], v[60:61]
	v_mov_b32_e32 v62, v37
	v_sub_f32_e32 v36, v40, v41
	v_add_u32_e32 v41, v42, v44
	v_cndmask_b32_e32 v40, v86, v36, vcc
	v_add_u32_e32 v36, 0x90, v41
	v_cvt_f32_i32_e32 v61, v36
	v_cmp_gt_u32_e32 vcc, s19, v36
	s_and_b64 vcc, s[10:11], vcc
	v_add_u32_e32 v44, -16, v44
	v_pk_mul_f32 v[36:37], v[62:63], v[60:61]
	v_mov_b32_e32 v62, v38
	v_sub_f32_e32 v36, v36, v37
	v_cndmask_b32_e32 v42, v86, v36, vcc
	v_add_u32_e32 v36, -2, v43
	v_cvt_f32_i32_e32 v61, v36
	v_cmp_gt_u32_e32 vcc, s19, v36
	s_and_b64 vcc, s[10:11], vcc
	v_max3_f32 v87, v53, v40, v42
	v_pk_mul_f32 v[36:37], v[62:63], v[60:61]
	v_mov_b32_e32 v62, v39
	v_sub_f32_e32 v36, v36, v37
	v_cndmask_b32_e32 v38, v86, v36, vcc
	v_add_u32_e32 v36, -3, v43
	v_cvt_f32_i32_e32 v61, v36
	v_cmp_gt_u32_e32 vcc, s19, v36
	s_and_b64 vcc, s[10:11], vcc
	v_pk_mul_f32 v[36:37], v[62:63], v[60:61]
	s_nop 0
	v_sub_f32_e32 v36, v36, v37
	v_cndmask_b32_e32 v39, v86, v36, vcc
	v_add_u32_e32 v36, -16, v43
	v_cvt_f32_i32_e32 v61, v36
	v_mov_b32_e32 v62, v28
	v_cmp_gt_u32_e32 vcc, s19, v36
	s_and_b64 vcc, vcc, s[6:7]
	v_pk_mul_f32 v[36:37], v[62:63], v[60:61]
	v_mov_b32_e32 v62, v29
	v_sub_f32_e32 v28, v36, v37
	v_cndmask_b32_e32 v36, v86, v28, vcc
	v_add_u32_e32 v28, 0x80, v41
	v_cvt_f32_i32_e32 v61, v28
	v_cmp_gt_u32_e32 vcc, s19, v28
	s_and_b64 vcc, vcc, s[6:7]
	v_max3_f32 v87, v87, v38, v39
	v_pk_mul_f32 v[28:29], v[62:63], v[60:61]
	v_mov_b32_e32 v62, v30
	v_sub_f32_e32 v28, v28, v29
	v_cndmask_b32_e32 v37, v86, v28, vcc
	v_subrev_u32_e32 v28, 18, v43
	v_cvt_f32_i32_e32 v61, v28
	v_cmp_gt_u32_e32 vcc, s19, v28
	s_and_b64 vcc, vcc, s[6:7]
	v_max3_f32 v87, v87, v36, v37
	v_pk_mul_f32 v[28:29], v[62:63], v[60:61]
	v_mov_b32_e32 v62, v31
	v_sub_f32_e32 v28, v28, v29
	v_cndmask_b32_e32 v30, v86, v28, vcc
	v_subrev_u32_e32 v28, 19, v43
	v_cvt_f32_i32_e32 v61, v28
	v_cmp_gt_u32_e32 vcc, s19, v28
	s_and_b64 vcc, vcc, s[6:7]
	v_cmp_lt_u32_e64 s[6:7], s27, v59
	v_pk_mul_f32 v[28:29], v[62:63], v[60:61]
	v_mov_b32_e32 v62, v24
	v_sub_f32_e32 v28, v28, v29
	v_cndmask_b32_e32 v31, v86, v28, vcc
	v_subrev_u32_e32 v28, 32, v43
	v_cvt_f32_i32_e32 v61, v28
	v_cmp_gt_u32_e32 vcc, s19, v28
	s_or_b64 s[6:7], s[10:11], s[6:7]
	s_and_b64 vcc, vcc, s[6:7]
	v_pk_mul_f32 v[28:29], v[62:63], v[60:61]
	v_mov_b32_e32 v62, v25
	v_sub_f32_e32 v24, v28, v29
	v_cndmask_b32_e32 v28, v86, v24, vcc
	v_add_u32_e32 v24, 0x70, v41
	v_cvt_f32_i32_e32 v61, v24
	v_cmp_gt_u32_e32 vcc, s19, v24
	s_and_b64 vcc, vcc, s[6:7]
	v_max3_f32 v87, v87, v30, v31
	v_pk_mul_f32 v[24:25], v[62:63], v[60:61]
	v_mov_b32_e32 v62, v26
	v_sub_f32_e32 v24, v24, v25
	v_cndmask_b32_e32 v29, v86, v24, vcc
	v_subrev_u32_e32 v24, 34, v43
	v_cvt_f32_i32_e32 v61, v24
	v_cmp_gt_u32_e32 vcc, s19, v24
	s_and_b64 vcc, vcc, s[6:7]
	v_max3_f32 v87, v87, v28, v29
	v_pk_mul_f32 v[24:25], v[62:63], v[60:61]
	v_mov_b32_e32 v62, v27
	v_sub_f32_e32 v24, v24, v25
	v_cndmask_b32_e32 v26, v86, v24, vcc
	v_subrev_u32_e32 v24, 35, v43
	v_cvt_f32_i32_e32 v61, v24
	v_cmp_gt_u32_e32 vcc, s19, v24
	s_and_b64 vcc, vcc, s[6:7]
	v_cmp_lt_u32_e64 s[6:7], s28, v59
	v_pk_mul_f32 v[24:25], v[62:63], v[60:61]
	v_mov_b32_e32 v62, v20
	v_sub_f32_e32 v24, v24, v25
	v_cndmask_b32_e32 v90, v86, v24, vcc
	v_subrev_u32_e32 v24, 48, v43
	v_cvt_f32_i32_e32 v61, v24
	v_cmp_gt_u32_e32 vcc, s19, v24
	s_or_b64 s[6:7], s[10:11], s[6:7]
	s_and_b64 vcc, vcc, s[6:7]
	v_pk_mul_f32 v[24:25], v[62:63], v[60:61]
	v_mov_b32_e32 v62, v21
	v_sub_f32_e32 v20, v24, v25
	v_cndmask_b32_e32 v24, v86, v20, vcc
	v_add_u32_e32 v20, 0x60, v41
	v_cvt_f32_i32_e32 v61, v20
	v_cmp_gt_u32_e32 vcc, s19, v20
	s_and_b64 vcc, vcc, s[6:7]
	v_max3_f32 v27, v87, v26, v90
	v_pk_mul_f32 v[20:21], v[62:63], v[60:61]
	v_mov_b32_e32 v62, v22
	v_sub_f32_e32 v20, v20, v21
	v_cndmask_b32_e32 v87, v86, v20, vcc
	v_subrev_u32_e32 v20, 50, v43
	v_cvt_f32_i32_e32 v61, v20
	v_cmp_gt_u32_e32 vcc, s19, v20
	s_and_b64 vcc, vcc, s[6:7]
	v_max3_f32 v25, v27, v24, v87
	v_pk_mul_f32 v[20:21], v[62:63], v[60:61]
	v_mov_b32_e32 v62, v23
	v_sub_f32_e32 v20, v20, v21
	v_cndmask_b32_e32 v22, v86, v20, vcc
	v_subrev_u32_e32 v20, 51, v43
	v_cvt_f32_i32_e32 v61, v20
	v_cmp_gt_u32_e32 vcc, s19, v20
	s_and_b64 vcc, vcc, s[6:7]
	v_cmp_lt_u32_e64 s[6:7], 48, v59
	v_pk_mul_f32 v[20:21], v[62:63], v[60:61]
	v_mov_b32_e32 v62, v16
	v_sub_f32_e32 v20, v20, v21
	v_cndmask_b32_e32 v23, v86, v20, vcc
	v_subrev_u32_e32 v20, 64, v43
	v_cvt_f32_i32_e32 v61, v20
	v_cmp_gt_u32_e32 vcc, s19, v20
	s_or_b64 s[6:7], s[10:11], s[6:7]
	s_and_b64 vcc, vcc, s[6:7]
	v_pk_mul_f32 v[20:21], v[62:63], v[60:61]
	v_mov_b32_e32 v62, v17
	v_sub_f32_e32 v16, v20, v21
	v_cndmask_b32_e32 v20, v86, v16, vcc
	v_add_u32_e32 v16, 0x50, v41
	v_cvt_f32_i32_e32 v61, v16
	v_cmp_gt_u32_e32 vcc, s19, v16
	s_and_b64 vcc, vcc, s[6:7]
	v_max3_f32 v25, v25, v22, v23
	v_pk_mul_f32 v[16:17], v[62:63], v[60:61]
	v_mov_b32_e32 v62, v18
	v_sub_f32_e32 v16, v16, v17
	v_cndmask_b32_e32 v21, v86, v16, vcc
	v_add_u32_e32 v16, 0xffffffbe, v43
	v_cvt_f32_i32_e32 v61, v16
	v_cmp_gt_u32_e32 vcc, s19, v16
	s_and_b64 vcc, vcc, s[6:7]
	v_max3_f32 v25, v25, v20, v21
	v_pk_mul_f32 v[16:17], v[62:63], v[60:61]
	v_mov_b32_e32 v62, v19
	v_sub_f32_e32 v16, v16, v17
	v_cndmask_b32_e32 v18, v86, v16, vcc
	v_add_u32_e32 v16, 0xffffffbd, v43
	v_cvt_f32_i32_e32 v61, v16
	v_cmp_gt_u32_e32 vcc, s19, v16
	s_and_b64 vcc, vcc, s[6:7]
	v_cmp_lt_u32_e64 s[6:7], 47, v59
	v_pk_mul_f32 v[16:17], v[62:63], v[60:61]
	v_mov_b32_e32 v62, v12
	v_sub_f32_e32 v16, v16, v17
	v_cndmask_b32_e32 v19, v86, v16, vcc
	v_add_u32_e32 v16, 0xffffffb0, v43
	v_cvt_f32_i32_e32 v61, v16
	v_cmp_gt_u32_e32 vcc, s19, v16
	s_or_b64 s[6:7], s[10:11], s[6:7]
	s_and_b64 vcc, vcc, s[6:7]
	v_pk_mul_f32 v[16:17], v[62:63], v[60:61]
	v_mov_b32_e32 v62, v13
	v_sub_f32_e32 v12, v16, v17
	v_cndmask_b32_e32 v16, v86, v12, vcc
	v_add_u32_e32 v12, 64, v41
	v_cvt_f32_i32_e32 v61, v12
	v_cmp_gt_u32_e32 vcc, s19, v12
	s_and_b64 vcc, vcc, s[6:7]
	v_max3_f32 v25, v25, v18, v19
	v_pk_mul_f32 v[12:13], v[62:63], v[60:61]
	v_mov_b32_e32 v62, v14
	v_sub_f32_e32 v12, v12, v13
	v_cndmask_b32_e32 v17, v86, v12, vcc
	v_add_u32_e32 v12, 0xffffffae, v43
	v_cvt_f32_i32_e32 v61, v12
	v_cmp_gt_u32_e32 vcc, s19, v12
	s_and_b64 vcc, vcc, s[6:7]
	v_max3_f32 v25, v25, v16, v17
	v_pk_mul_f32 v[12:13], v[62:63], v[60:61]
	v_mov_b32_e32 v62, v15
	v_sub_f32_e32 v12, v12, v13
	v_cndmask_b32_e32 v14, v86, v12, vcc
	v_add_u32_e32 v12, 0xffffffad, v43
	v_cvt_f32_i32_e32 v61, v12
	v_cmp_gt_u32_e32 vcc, s19, v12
	s_and_b64 vcc, vcc, s[6:7]
	v_cmp_lt_u32_e64 s[6:7], 16, v59
	v_pk_mul_f32 v[12:13], v[62:63], v[60:61]
	v_mov_b32_e32 v62, v8
	v_sub_f32_e32 v12, v12, v13
	v_cndmask_b32_e32 v15, v86, v12, vcc
	v_add_u32_e32 v12, 0xffffffa0, v43
	v_cvt_f32_i32_e32 v61, v12
	v_cmp_gt_u32_e32 vcc, s19, v12
	s_or_b64 s[6:7], s[10:11], s[6:7]
	s_and_b64 vcc, vcc, s[6:7]
	v_pk_mul_f32 v[12:13], v[62:63], v[60:61]
	v_mov_b32_e32 v62, v9
	v_sub_f32_e32 v8, v12, v13
	v_cndmask_b32_e32 v12, v86, v8, vcc
	v_add_u32_e32 v8, 48, v41
	v_cvt_f32_i32_e32 v61, v8
	v_cmp_gt_u32_e32 vcc, s19, v8
	s_and_b64 vcc, vcc, s[6:7]
	v_max3_f32 v25, v25, v14, v15
	v_pk_mul_f32 v[8:9], v[62:63], v[60:61]
	v_mov_b32_e32 v62, v10
	v_sub_f32_e32 v8, v8, v9
	v_cndmask_b32_e32 v13, v86, v8, vcc
	v_add_u32_e32 v8, 0xffffff9e, v43
	v_cvt_f32_i32_e32 v61, v8
	v_cmp_gt_u32_e32 vcc, s19, v8
	s_and_b64 vcc, vcc, s[6:7]
	v_max3_f32 v25, v25, v12, v13
	v_pk_mul_f32 v[8:9], v[62:63], v[60:61]
	v_mov_b32_e32 v62, v11
	v_sub_f32_e32 v8, v8, v9
	v_cndmask_b32_e32 v10, v86, v8, vcc
	v_add_u32_e32 v8, 0xffffff9d, v43
	v_cvt_f32_i32_e32 v61, v8
	v_cmp_gt_u32_e32 vcc, s19, v8
	s_and_b64 vcc, vcc, s[6:7]
	v_pk_mul_f32 v[8:9], v[62:63], v[60:61]
	s_nop 0
	v_sub_f32_e32 v8, v8, v9
	v_cndmask_b32_e32 v11, v86, v8, vcc
	v_add_u32_e32 v8, 0xffffff90, v43
	v_cvt_f32_i32_e32 v61, v8
	v_or_b32_e32 v9, s30, v59
	v_mov_b32_e32 v62, v4
	v_cmp_gt_u32_e32 vcc, s19, v8
	v_cmp_ne_u32_e64 s[6:7], 0, v9
	v_pk_mul_f32 v[8:9], v[62:63], v[60:61]
	s_and_b64 vcc, s[6:7], vcc
	v_sub_f32_e32 v4, v8, v9
	v_cndmask_b32_e32 v8, v86, v4, vcc
	v_add_u32_e32 v4, 32, v41
	v_cvt_f32_i32_e32 v61, v4
	v_mov_b32_e32 v62, v5
	v_cmp_gt_u32_e32 vcc, s19, v4
	s_and_b64 vcc, s[6:7], vcc
	v_pk_mul_f32 v[4:5], v[62:63], v[60:61]
	v_mov_b32_e32 v62, v6
	v_sub_f32_e32 v4, v4, v5
	v_cndmask_b32_e32 v9, v86, v4, vcc
	v_add_u32_e32 v4, 0xffffff8e, v43
	v_cvt_f32_i32_e32 v61, v4
	v_cmp_gt_u32_e32 vcc, s19, v4
	s_and_b64 vcc, s[6:7], vcc
	v_max3_f32 v25, v25, v10, v11
	v_pk_mul_f32 v[4:5], v[62:63], v[60:61]
	v_mov_b32_e32 v62, v7
	v_sub_f32_e32 v4, v4, v5
	v_cndmask_b32_e32 v6, v86, v4, vcc
	v_add_u32_e32 v4, 0xffffff8d, v43
	v_cvt_f32_i32_e32 v61, v4
	v_cmp_gt_u32_e32 vcc, s19, v4
	s_and_b64 vcc, s[6:7], vcc
	v_max3_f32 v25, v25, v8, v9
	v_pk_mul_f32 v[4:5], v[62:63], v[60:61]
	v_mov_b32_e32 v62, v0
	v_sub_f32_e32 v4, v4, v5
	v_cndmask_b32_e32 v7, v86, v4, vcc
	v_add_u32_e32 v4, 0xffffff80, v43
	v_cvt_f32_i32_e32 v61, v4
	v_cmp_gt_u32_e32 vcc, s19, v4
	v_max3_f32 v25, v25, v6, v7
	s_cmp_lg_u32 s33, 64
	v_pk_mul_f32 v[4:5], v[62:63], v[60:61]
	v_mov_b32_e32 v62, v1
	v_sub_f32_e32 v0, v4, v5
	v_cndmask_b32_e32 v4, v86, v0, vcc
	v_add_u32_e32 v0, 16, v41
	v_cvt_f32_i32_e32 v61, v0
	v_cmp_gt_u32_e32 vcc, s19, v0
	v_pk_mul_f32 v[0:1], v[62:63], v[60:61]
	s_nop 0
	v_sub_f32_e32 v0, v0, v1
	v_cndmask_b32_e32 v5, v86, v0, vcc
	v_add_u32_e32 v0, 0xffffff7e, v43
	v_cvt_f32_i32_e32 v61, v0
	v_mov_b32_e32 v62, v2
	v_cmp_gt_u32_e32 vcc, s19, v0
	v_max3_f32 v25, v25, v4, v5
	v_pk_mul_f32 v[0:1], v[62:63], v[60:61]
	v_mov_b32_e32 v62, v3
	v_sub_f32_e32 v0, v0, v1
	v_cndmask_b32_e32 v2, v86, v0, vcc
	v_add_u32_e32 v0, 0xffffff7d, v43
	v_cvt_f32_i32_e32 v61, v0
	v_cmp_gt_u32_e32 vcc, s19, v0
	v_pk_mul_f32 v[0:1], v[62:63], v[60:61]
	s_nop 0
	v_sub_f32_e32 v0, v0, v1
	v_cndmask_b32_e32 v3, v86, v0, vcc
	v_add_u32_e32 v0, 0xffffff70, v43
	v_cvt_f32_i32_e32 v61, v0
	v_mov_b32_e32 v62, v32
	v_cmp_gt_u32_e32 vcc, s19, v0
	v_max3_f32 v25, v25, v2, v3
	v_pk_mul_f32 v[0:1], v[62:63], v[60:61]
	v_cvt_f32_i32_e32 v61, v41
	v_sub_f32_e32 v0, v0, v1
	v_mov_b32_e32 v62, v33
	v_cndmask_b32_e32 v59, v86, v0, vcc
	v_pk_mul_f32 v[0:1], v[62:63], v[60:61]
	v_cmp_gt_u32_e32 vcc, s19, v41
	v_sub_f32_e32 v0, v0, v1
	v_mov_b32_e32 v62, v34
	v_cndmask_b32_e32 v41, v86, v0, vcc
	v_add_u32_e32 v0, 0xffffff6e, v43
	v_cvt_f32_i32_e32 v61, v0
	v_cmp_gt_u32_e32 vcc, s19, v0
	v_max3_f32 v25, v25, v59, v41
	v_pk_mul_f32 v[0:1], v[62:63], v[60:61]
	s_nop 0
	v_sub_f32_e32 v0, v0, v1
	v_cndmask_b32_e32 v91, v86, v0, vcc
	v_add_u32_e32 v0, 0xffffff6d, v43
	v_cvt_f32_i32_e32 v61, v0
	v_mov_b32_e32 v62, v35
	v_cmp_gt_u32_e32 vcc, s19, v0
	v_pk_mul_f32 v[0:1], v[62:63], v[60:61]
	s_nop 0
	v_sub_f32_e32 v0, v0, v1
	v_cndmask_b32_e32 v0, v86, v0, vcc
	v_max3_f32 v1, v25, v91, v0
	ds_bpermute_b32 v25, v76, v1
	s_waitcnt lgkmcnt(0)
	v_max_f32_e32 v25, v25, v25
	v_max_f32_e32 v1, v1, v25
	ds_bpermute_b32 v25, v77, v1
	s_waitcnt lgkmcnt(0)
	v_max_f32_e32 v25, v25, v25
	v_max_f32_e32 v1, v1, v25
	v_sub_f32_e32 v27, v42, v1
	v_mul_f32_e32 v27, 0x3fb8aa3b, v27
	v_exp_f32_e32 v42, v27
	v_sub_f32_e32 v27, v38, v1
	v_mul_f32_e32 v27, 0x3fb8aa3b, v27
	v_exp_f32_e32 v38, v27
	v_sub_f32_e32 v27, v39, v1
	v_sub_f32_e32 v25, v40, v1
	v_mul_f32_e32 v27, 0x3fb8aa3b, v27
	v_mul_f32_e32 v25, 0x3fb8aa3b, v25
	v_exp_f32_e32 v39, v27
	v_sub_f32_e32 v27, v36, v1
	v_exp_f32_e32 v40, v25
	v_mul_f32_e32 v27, 0x3fb8aa3b, v27
	v_exp_f32_e32 v43, v27
	v_sub_f32_e32 v27, v37, v1
	v_mul_f32_e32 v27, 0x3fb8aa3b, v27
	v_exp_f32_e32 v61, v27
	v_sub_f32_e32 v27, v30, v1
	v_add_f32_e32 v25, 0, v40
	v_mul_f32_e32 v27, 0x3fb8aa3b, v27
	v_add_f32_e32 v25, v42, v25
	v_exp_f32_e32 v62, v27
	v_sub_f32_e32 v27, v31, v1
	v_add_f32_e32 v25, v38, v25
	v_mul_f32_e32 v27, 0x3fb8aa3b, v27
	v_add_f32_e32 v25, v39, v25
	v_exp_f32_e32 v92, v27
	v_add_f32_e32 v25, v43, v25
	v_add_f32_e32 v25, v61, v25
	v_add_f32_e32 v25, v62, v25
	v_add_f32_e32 v27, v92, v25
	v_sub_f32_e32 v25, v28, v1
	v_mul_f32_e32 v25, 0x3fb8aa3b, v25
	v_exp_f32_e32 v25, v25
	v_sub_f32_e32 v26, v26, v1
	v_mul_f32_e32 v26, 0x3fb8aa3b, v26
	v_sub_f32_e32 v24, v24, v1
	v_add_f32_e32 v28, v25, v27
	v_sub_f32_e32 v27, v29, v1
	v_mul_f32_e32 v27, 0x3fb8aa3b, v27
	v_exp_f32_e32 v27, v27
	v_exp_f32_e32 v29, v26
	v_mul_f32_e32 v24, 0x3fb8aa3b, v24
	v_exp_f32_e32 v33, v24
	v_add_f32_e32 v28, v27, v28
	v_add_f32_e32 v26, v29, v28
	v_sub_f32_e32 v28, v90, v1
	v_mul_f32_e32 v28, 0x3fb8aa3b, v28
	v_exp_f32_e32 v31, v28
	v_sub_f32_e32 v22, v22, v1
	v_mul_f32_e32 v22, 0x3fb8aa3b, v22
	v_sub_f32_e32 v23, v23, v1
	v_add_f32_e32 v26, v31, v26
	v_add_f32_e32 v24, v33, v26
	v_sub_f32_e32 v26, v87, v1
	v_mul_f32_e32 v26, 0x3fb8aa3b, v26
	v_exp_f32_e32 v35, v26
	v_exp_f32_e32 v36, v22
	v_mul_f32_e32 v23, 0x3fb8aa3b, v23
	v_exp_f32_e32 v37, v23
	v_add_f32_e32 v24, v35, v24
	v_sub_f32_e32 v20, v20, v1
	v_add_f32_e32 v22, v36, v24
	v_mul_f32_e32 v20, 0x3fb8aa3b, v20
	v_add_f32_e32 v23, v37, v22
	v_exp_f32_e32 v22, v20
	v_sub_f32_e32 v21, v21, v1
	v_mul_f32_e32 v21, 0x3fb8aa3b, v21
	v_sub_f32_e32 v18, v18, v1
	v_add_f32_e32 v20, v22, v23
	v_exp_f32_e32 v23, v21
	v_mul_f32_e32 v18, 0x3fb8aa3b, v18
	v_sub_f32_e32 v19, v19, v1
	v_exp_f32_e32 v24, v18
	v_mul_f32_e32 v19, 0x3fb8aa3b, v19
	v_sub_f32_e32 v16, v16, v1
	v_exp_f32_e32 v26, v19
	v_mul_f32_e32 v16, 0x3fb8aa3b, v16
	v_sub_f32_e32 v17, v17, v1
	v_exp_f32_e32 v28, v16
	v_mul_f32_e32 v17, 0x3fb8aa3b, v17
	v_sub_f32_e32 v14, v14, v1
	v_add_f32_e32 v20, v23, v20
	v_exp_f32_e32 v30, v17
	v_mul_f32_e32 v14, 0x3fb8aa3b, v14
	v_sub_f32_e32 v15, v15, v1
	v_add_f32_e32 v18, v24, v20
	v_exp_f32_e32 v32, v14
	v_mul_f32_e32 v15, 0x3fb8aa3b, v15
	v_add_f32_e32 v18, v26, v18
	v_exp_f32_e32 v34, v15
	v_add_f32_e32 v16, v28, v18
	v_add_f32_e32 v16, v30, v16
	v_sub_f32_e32 v12, v12, v1
	v_add_f32_e32 v14, v32, v16
	v_mul_f32_e32 v12, 0x3fb8aa3b, v12
	v_add_f32_e32 v15, v34, v14
	v_exp_f32_e32 v14, v12
	v_sub_f32_e32 v13, v13, v1
	v_mul_f32_e32 v13, 0x3fb8aa3b, v13
	v_sub_f32_e32 v10, v10, v1
	v_add_f32_e32 v12, v14, v15
	v_exp_f32_e32 v15, v13
	v_mul_f32_e32 v10, 0x3fb8aa3b, v10
	v_sub_f32_e32 v11, v11, v1
	v_exp_f32_e32 v16, v10
	v_mul_f32_e32 v11, 0x3fb8aa3b, v11
	v_sub_f32_e32 v8, v8, v1
	v_exp_f32_e32 v17, v11
	v_mul_f32_e32 v8, 0x3fb8aa3b, v8
	v_sub_f32_e32 v9, v9, v1
	v_exp_f32_e32 v18, v8
	v_mul_f32_e32 v9, 0x3fb8aa3b, v9
	v_sub_f32_e32 v6, v6, v1
	v_add_f32_e32 v12, v15, v12
	v_exp_f32_e32 v19, v9
	v_mul_f32_e32 v6, 0x3fb8aa3b, v6
	v_sub_f32_e32 v7, v7, v1
	v_add_f32_e32 v10, v16, v12
	v_exp_f32_e32 v20, v6
	v_mul_f32_e32 v7, 0x3fb8aa3b, v7
	v_add_f32_e32 v10, v17, v10
	v_exp_f32_e32 v21, v7
	v_add_f32_e32 v8, v18, v10
	v_add_f32_e32 v8, v19, v8
	v_sub_f32_e32 v4, v4, v1
	v_add_f32_e32 v6, v20, v8
	v_mul_f32_e32 v4, 0x3fb8aa3b, v4
	v_add_f32_e32 v7, v21, v6
	v_exp_f32_e32 v6, v4
	v_sub_f32_e32 v3, v3, v1
	v_sub_f32_e32 v5, v5, v1
	v_mul_f32_e32 v3, 0x3fb8aa3b, v3
	v_mul_f32_e32 v5, 0x3fb8aa3b, v5
	v_sub_f32_e32 v2, v2, v1
	v_exp_f32_e32 v9, v3
	v_sub_f32_e32 v3, v59, v1
	v_add_f32_e32 v4, v6, v7
	v_exp_f32_e32 v7, v5
	v_mul_f32_e32 v2, 0x3fb8aa3b, v2
	v_mul_f32_e32 v3, 0x3fb8aa3b, v3
	v_exp_f32_e32 v8, v2
	v_exp_f32_e32 v10, v3
	v_sub_f32_e32 v3, v41, v1
	v_mul_f32_e32 v3, 0x3fb8aa3b, v3
	v_exp_f32_e32 v11, v3
	v_sub_f32_e32 v3, v91, v1
	v_add_f32_e32 v4, v7, v4
	v_mul_f32_e32 v3, 0x3fb8aa3b, v3
	v_sub_f32_e32 v0, v0, v1
	v_add_f32_e32 v2, v8, v4
	v_exp_f32_e32 v12, v3
	v_mul_f32_e32 v0, 0x3fb8aa3b, v0
	v_add_f32_e32 v2, v9, v2
	v_exp_f32_e32 v13, v0
	v_add_f32_e32 v2, v10, v2
	v_add_f32_e32 v2, v11, v2
	v_add_f32_e32 v2, v12, v2
	v_add_f32_e32 v0, v13, v2
	ds_bpermute_b32 v2, v76, v0
	v_sub_f32_e32 v1, v53, v1
	v_mul_f32_e32 v1, 0x3fb8aa3b, v1
	v_exp_f32_e32 v4, v1
	v_cvt_pk_bf16_f32 v1, v38, v39
	s_waitcnt lgkmcnt(0)
	v_add_f32_e32 v0, v0, v2
	ds_bpermute_b32 v2, v77, v0
	v_add_u32_e32 v39, 0x2000, v57
	v_add_u32_e32 v59, 0x4800, v57
	v_cvt_pk_bf16_f32 v3, v62, v92
	ds_read2_b64 v[90:93], v39 offset0:160 offset1:164
	s_waitcnt lgkmcnt(1)
	v_add_f32_e32 v5, v0, v2
	v_cvt_pk_bf16_f32 v0, v40, v42
	v_cvt_pk_bf16_f32 v2, v43, v61
	ds_read2_b64 v[40:43], v57 offset1:4
	v_add_u32_e32 v61, 0x6800, v57
	ds_read2_b64 v[98:101], v59 offset0:64 offset1:68
	ds_read2_b64 v[102:105], v61 offset0:224 offset1:228
	s_waitcnt lgkmcnt(2)
	v_mfma_f32_16x16x32_bf16 v[40:43], v[40:43], v[0:3], 0
	v_cvt_pk_bf16_f32 v22, v22, v23
	v_cvt_pk_bf16_f32 v23, v24, v26
	v_cvt_pk_bf16_f32 v24, v28, v30
	v_mfma_f32_16x16x32_bf16 v[90:93], v[90:93], v[0:3], 0
	v_cvt_pk_bf16_f32 v14, v14, v15
	v_cvt_pk_bf16_f32 v15, v16, v17
	v_cvt_pk_bf16_f32 v16, v18, v19
	s_waitcnt lgkmcnt(1)
	v_mfma_f32_16x16x32_bf16 v[98:101], v[98:101], v[0:3], 0
	v_cvt_pk_bf16_f32 v17, v20, v21
	ds_read2_b64 v[18:21], v57 offset0:24 offset1:28
	v_cvt_pk_bf16_f32 v6, v6, v7
	s_waitcnt lgkmcnt(1)
	v_mfma_f32_16x16x32_bf16 v[0:3], v[102:105], v[0:3], 0
	v_cvt_pk_bf16_f32 v102, v25, v27
	v_cvt_pk_bf16_f32 v103, v29, v31
	v_cvt_pk_bf16_f32 v104, v33, v35
	v_cvt_pk_bf16_f32 v105, v36, v37
	ds_read2_b64 v[26:29], v57 offset0:16 offset1:20
	v_cvt_pk_bf16_f32 v25, v32, v34
	v_mfma_f32_16x16x32_bf16 v[40:43], v[106:109], v[102:105], v[40:43]
	ds_read2_b64 v[106:109], v39 offset0:168 offset1:172
	ds_read2_b64 v[30:33], v39 offset0:176 offset1:180
	ds_read2_b64 v[34:37], v59 offset0:80 offset1:84
	s_waitcnt lgkmcnt(2)
	v_mfma_f32_16x16x32_bf16 v[90:93], v[106:109], v[102:105], v[90:93]
	ds_read2_b64 v[106:109], v59 offset0:72 offset1:76
	v_cvt_pk_bf16_f32 v7, v8, v9
	v_cvt_pk_bf16_f32 v8, v10, v11
	s_waitcnt lgkmcnt(0)
	v_mfma_f32_16x16x32_bf16 v[98:101], v[106:109], v[102:105], v[98:101]
	ds_read2_b64 v[106:109], v61 offset0:232 offset1:236
	v_cvt_pk_bf16_f32 v9, v12, v13
	ds_read2_b64 v[10:13], v57 offset0:32 offset1:36
	v_mfma_f32_16x16x32_bf16 v[26:29], v[26:29], v[22:25], v[40:43]
	v_add_f32_e32 v4, v4, v5
	v_div_scale_f32 v5, s[6:7], v4, v4, 1.0
	s_nop 0
	ds_read2_b64 v[40:43], v61 offset0:240 offset1:244
	s_waitcnt lgkmcnt(2)
	v_mfma_f32_16x16x32_bf16 v[0:3], v[106:109], v[102:105], v[0:3]
	v_add_u32_e32 v38, 32, v57
	v_mfma_f32_16x16x32_bf16 v[30:33], v[30:33], v[22:25], v[90:93]
	v_mfma_f32_16x16x32_bf16 v[34:37], v[34:37], v[22:25], v[98:101]
	s_waitcnt lgkmcnt(0)
	v_mfma_f32_16x16x32_bf16 v[0:3], v[40:43], v[22:25], v[0:3]
	ds_read2_b64 v[22:25], v39 offset0:184 offset1:188
	v_mfma_f32_16x16x32_bf16 v[18:21], v[18:21], v[14:17], v[26:29]
	s_waitcnt lgkmcnt(0)
	v_mfma_f32_16x16x32_bf16 v[22:25], v[22:25], v[14:17], v[30:33]
	s_nop 0
	ds_read2_b64 v[26:29], v59 offset0:88 offset1:92
	s_nop 0
	ds_read2_b64 v[30:33], v61 offset0:248 offset1:252
	s_waitcnt lgkmcnt(1)
	v_mfma_f32_16x16x32_bf16 v[26:29], v[26:29], v[14:17], v[34:37]
	s_waitcnt lgkmcnt(0)
	v_mfma_f32_16x16x32_bf16 v[0:3], v[30:33], v[14:17], v[0:3]
	ds_read2_b64 v[14:17], v39 offset0:192 offset1:196
	s_waitcnt lgkmcnt(0)
	v_mfma_f32_16x16x32_bf16 v[14:17], v[14:17], v[6:9], v[22:25]
	s_nop 2
	v_add_u32_e32 v22, 0x7000, v57
	ds_read2_b64 v[22:25], v22 offset1:4
	v_mov_b32_e32 v57, v38
	v_mfma_f32_16x16x32_bf16 v[10:13], v[10:13], v[6:9], v[18:21]
	s_nop 2
	ds_read2_b64 v[18:21], v59 offset0:96 offset1:100
	s_waitcnt lgkmcnt(0)
	v_mfma_f32_16x16x32_bf16 v[18:21], v[18:21], v[6:9], v[26:29]
	v_mfma_f32_16x16x32_bf16 v[0:3], v[22:25], v[6:9], v[0:3]
	v_rcp_f32_e32 v6, v5
	s_nop 0
	v_fma_f32 v7, -v5, v6, 1.0
	v_fmac_f32_e32 v6, v7, v6
	v_div_scale_f32 v7, vcc, 1.0, v4, 1.0
	v_mul_f32_e32 v8, v7, v6
	v_fma_f32 v9, -v5, v8, v7
	v_fmac_f32_e32 v8, v9, v6
	v_fma_f32 v5, -v5, v8, v7
	v_div_fmas_f32 v5, v5, v6, v8
	v_div_fixup_f32 v4, v5, v4, 1.0
	v_lshlrev_b64 v[6:7], 11, v[72:73]
	v_pk_mul_f32 v[8:9], v[10:11], v[4:5] op_sel_hi:[1,0]
	v_pk_mul_f32 v[10:11], v[12:13], v[4:5] op_sel_hi:[1,0]
	v_lshl_add_u64 v[6:7], v[68:69], 0, v[6:7]
	v_cvt_pk_bf16_f32 v8, v8, v9
	v_cvt_pk_bf16_f32 v9, v10, v11
	global_store_dwordx2 v[6:7], v[8:9], off
	v_pk_mul_f32 v[8:9], v[4:5], v[14:15] op_sel_hi:[0,1]
	v_pk_mul_f32 v[10:11], v[4:5], v[16:17] op_sel_hi:[0,1]
	v_cvt_pk_bf16_f32 v8, v8, v9
	v_cvt_pk_bf16_f32 v9, v10, v11
	global_store_dwordx2 v[6:7], v[8:9], off offset:32
	v_pk_mul_f32 v[8:9], v[4:5], v[18:19] op_sel_hi:[0,1]
	v_pk_mul_f32 v[10:11], v[4:5], v[20:21] op_sel_hi:[0,1]
	v_pk_mul_f32 v[0:1], v[4:5], v[0:1] op_sel_hi:[0,1]
	v_pk_mul_f32 v[2:3], v[4:5], v[2:3] op_sel_hi:[0,1]
	v_cvt_pk_bf16_f32 v8, v8, v9
	v_cvt_pk_bf16_f32 v9, v10, v11
	v_cvt_pk_bf16_f32 v0, v0, v1
	v_cvt_pk_bf16_f32 v1, v2, v3
	global_store_dwordx2 v[6:7], v[8:9], off offset:64
	global_store_dwordx2 v[6:7], v[0:1], off offset:96
	s_cbranch_scc1 .LBB0_985
	s_add_i32 s29, s29, s94
	s_add_i32 s14, s14, s15
	s_cmpk_gt_i32 s29, 0xff
	s_barrier
	s_cbranch_scc0 .LBB0_976

.LBB0_1564:
	v_and_b32_e32 v254, 63, v128
	v_and_b32_e32 v255, 3, v254
	v_lshrrev_b32_e32 v254, 2, v254
	v_lshl_or_b32 v254, v255, 4, v254
	v_lshlrev_b32_e32 v254, 2, v254
	s_cmp_lt_i32 s14, 2
	s_cselect_b32 s23, s60, 0x1aa05000
	s_add_u32 s23, s50, s23
	s_addc_u32 s29, s51, 0
	s_bitcmp1_b32 s14, 0
	s_cselect_b32 s14, 0x2400000, 0
	s_add_u32 s38, s23, s14
	v_lshl_or_b32 v152, s24, 8, v147
	v_lshl_add_u32 v154, s26, 8, v129
	s_addc_u32 s39, s29, 0
	v_ashrrev_i32_e32 v153, 31, v152
	v_ashrrev_i32_e32 v155, 31, v154
	v_lshl_add_u64 v[152:153], v[152:153], 1, s[38:39]
	v_lshlrev_b64 v[156:157], 12, v[154:155]
	v_lshl_add_u64 v[156:157], v[152:153], 0, v[156:157]
	v_cvt_pk_bf16_f32 v60, v60, v61
	v_cvt_pk_bf16_f32 v61, v62, v63
	v_cvt_pk_bf16_f32 v62, v56, v57
	v_add_co_u32_e32 v56, vcc, s61, v156
	v_cvt_pk_bf16_f32 v68, v68, v69
	v_cvt_pk_bf16_f32 v69, v70, v71
	v_cvt_pk_bf16_f32 v70, v64, v65
	v_lshl_add_u64 v[64:65], v[156:157], 0, s[0:1]
	v_addc_co_u32_e32 v57, vcc, 0, v157, vcc
	v_cvt_pk_bf16_f32 v44, v44, v45
	v_cvt_pk_bf16_f32 v45, v46, v47
	v_cvt_pk_bf16_f32 v46, v40, v41
	v_cvt_pk_bf16_f32 v47, v42, v43
	ds_bpermute_b32 v238, v254, v44
	ds_bpermute_b32 v239, v254, v45
	ds_bpermute_b32 v240, v254, v46
	ds_bpermute_b32 v241, v254, v47
	ds_bpermute_b32 v236, v254, v64
	ds_bpermute_b32 v237, v254, v65
	v_cvt_pk_bf16_f32 v108, v108, v109
	v_cvt_pk_bf16_f32 v109, v110, v111
	v_add_co_u32_e32 v46, vcc, s62, v156
	v_cvt_pk_bf16_f32 v110, v104, v105
	v_or_b32_e32 v104, 16, v154
	v_lshl_add_u64 v[44:45], v[156:157], 0, s[16:17]
	v_addc_co_u32_e32 v47, vcc, 0, v157, vcc
	v_cvt_pk_bf16_f32 v28, v28, v29
	v_cvt_pk_bf16_f32 v29, v30, v31
	v_cvt_pk_bf16_f32 v30, v24, v25
	v_cvt_pk_bf16_f32 v31, v26, v27
	v_ashrrev_i32_e32 v105, 31, v104
	v_cvt_pk_bf16_f32 v92, v92, v93
	v_cvt_pk_bf16_f32 v93, v94, v95
	v_cvt_pk_bf16_f32 v94, v88, v89
	v_or_b32_e32 v88, 32, v154
	ds_bpermute_b32 v244, v254, v28
	ds_bpermute_b32 v245, v254, v29
	ds_bpermute_b32 v246, v254, v30
	ds_bpermute_b32 v247, v254, v31
	ds_bpermute_b32 v242, v254, v44
	ds_bpermute_b32 v243, v254, v45
	v_cvt_pk_bf16_f32 v111, v106, v107
	v_lshlrev_b64 v[104:105], 12, v[104:105]
	v_add_co_u32_e32 v30, vcc, s63, v156
	v_ashrrev_i32_e32 v89, 31, v88
	v_cvt_pk_bf16_f32 v76, v76, v77
	v_cvt_pk_bf16_f32 v77, v78, v79
	v_cvt_pk_bf16_f32 v78, v72, v73
	v_or_b32_e32 v72, 48, v154
	v_lshl_add_u64 v[28:29], v[156:157], 0, s[18:19]
	v_addc_co_u32_e32 v31, vcc, 0, v157, vcc
	v_cvt_pk_bf16_f32 v12, v12, v13
	v_cvt_pk_bf16_f32 v13, v14, v15
	v_cvt_pk_bf16_f32 v14, v8, v9
	v_cvt_pk_bf16_f32 v15, v10, v11
	ds_bpermute_b32 v250, v254, v108
	ds_bpermute_b32 v251, v254, v109
	ds_bpermute_b32 v252, v254, v110
	ds_bpermute_b32 v253, v254, v111
	ds_bpermute_b32 v248, v254, v156
	ds_bpermute_b32 v249, v254, v157
	v_cvt_pk_bf16_f32 v95, v90, v91
	v_lshlrev_b64 v[88:89], 12, v[88:89]
	v_lshl_add_u64 v[108:109], v[152:153], 0, v[104:105]
	v_ashrrev_i32_e32 v73, 31, v72
	s_waitcnt lgkmcnt(12)
	global_store_dwordx4 v[236:237], v[238:241], off offset:256
	s_nop 0
	ds_bpermute_b32 v238, v254, v12
	ds_bpermute_b32 v239, v254, v13
	ds_bpermute_b32 v240, v254, v14
	ds_bpermute_b32 v241, v254, v15
	ds_bpermute_b32 v236, v254, v28
	ds_bpermute_b32 v237, v254, v29
	s_waitcnt lgkmcnt(12)
	global_store_dwordx4 v[242:243], v[244:247], off offset:256
	s_nop 0
	ds_bpermute_b32 v244, v254, v92
	ds_bpermute_b32 v245, v254, v93
	ds_bpermute_b32 v246, v254, v94
	ds_bpermute_b32 v247, v254, v95
	ds_bpermute_b32 v242, v254, v108
	ds_bpermute_b32 v243, v254, v109
	v_cvt_pk_bf16_f32 v79, v74, v75
	v_add_co_u32_e32 v14, vcc, s64, v156
	v_lshl_add_u64 v[92:93], v[152:153], 0, v[88:89]
	v_lshlrev_b64 v[72:73], 12, v[72:73]
	v_addc_co_u32_e32 v15, vcc, 0, v157, vcc
	v_cvt_pk_bf16_f32 v124, v124, v125
	v_cvt_pk_bf16_f32 v125, v126, v127
	v_cvt_pk_bf16_f32 v126, v120, v121
	v_cvt_pk_bf16_f32 v127, v122, v123
	v_cvt_pk_bf16_f32 v104, v116, v117
	v_cvt_pk_bf16_f32 v105, v118, v119
	v_cvt_pk_bf16_f32 v106, v112, v113
	v_cvt_pk_bf16_f32 v107, v114, v115
	v_cvt_pk_bf16_f32 v88, v100, v101
	v_cvt_pk_bf16_f32 v89, v102, v103
	v_cvt_pk_bf16_f32 v90, v96, v97
	v_cvt_pk_bf16_f32 v91, v98, v99
	s_waitcnt lgkmcnt(12)
	global_store_dwordx4 v[248:249], v[250:253], off offset:256
	s_nop 0
	ds_bpermute_b32 v250, v254, v76
	ds_bpermute_b32 v251, v254, v77
	ds_bpermute_b32 v252, v254, v78
	ds_bpermute_b32 v253, v254, v79
	ds_bpermute_b32 v248, v254, v92
	ds_bpermute_b32 v249, v254, v93
	v_cvt_pk_bf16_f32 v74, v80, v81
	v_cvt_pk_bf16_f32 v75, v82, v83
	v_lshl_add_u64 v[76:77], v[152:153], 0, v[72:73]
	v_cvt_pk_bf16_f32 v72, v84, v85
	v_cvt_pk_bf16_f32 v73, v86, v87
	v_cvt_pk_bf16_f32 v71, v66, v67
	v_cvt_pk_bf16_f32 v63, v58, v59
	v_cvt_pk_bf16_f32 v40, v52, v53
	v_cvt_pk_bf16_f32 v41, v54, v55
	v_cvt_pk_bf16_f32 v42, v48, v49
	v_cvt_pk_bf16_f32 v43, v50, v51
	v_cvt_pk_bf16_f32 v24, v36, v37
	v_cvt_pk_bf16_f32 v25, v38, v39
	v_cvt_pk_bf16_f32 v26, v32, v33
	v_cvt_pk_bf16_f32 v27, v34, v35
	v_lshl_add_u64 v[12:13], v[156:157], 0, s[20:21]
	v_cvt_pk_bf16_f32 v8, v20, v21
	v_cvt_pk_bf16_f32 v9, v22, v23
	v_cvt_pk_bf16_f32 v10, v16, v17
	v_cvt_pk_bf16_f32 v11, v18, v19
	v_cvt_pk_bf16_f32 v4, v4, v5
	v_cvt_pk_bf16_f32 v5, v6, v7
	v_cvt_pk_bf16_f32 v6, v0, v1
	v_cvt_pk_bf16_f32 v7, v2, v3
	s_and_b64 vcc, exec, s[4:5]
	s_mov_b64 s[4:5], -1
	s_waitcnt lgkmcnt(12)
	global_store_dwordx4 v[236:237], v[238:241], off offset:256
	s_nop 0
	ds_bpermute_b32 v238, v254, v124
	ds_bpermute_b32 v239, v254, v125
	ds_bpermute_b32 v240, v254, v126
	ds_bpermute_b32 v241, v254, v127
	ds_bpermute_b32 v236, v254, v156
	ds_bpermute_b32 v237, v254, v157
	s_waitcnt lgkmcnt(12)
	global_store_dwordx4 v[242:243], v[244:247], off offset:256
	s_nop 0
	ds_bpermute_b32 v244, v254, v104
	ds_bpermute_b32 v245, v254, v105
	ds_bpermute_b32 v246, v254, v106
	ds_bpermute_b32 v247, v254, v107
	ds_bpermute_b32 v242, v254, v108
	ds_bpermute_b32 v243, v254, v109
	s_waitcnt lgkmcnt(12)
	global_store_dwordx4 v[248:249], v[250:253], off offset:256
	s_nop 0
	ds_bpermute_b32 v250, v254, v88
	ds_bpermute_b32 v251, v254, v89
	ds_bpermute_b32 v252, v254, v90
	ds_bpermute_b32 v253, v254, v91
	ds_bpermute_b32 v248, v254, v92
	ds_bpermute_b32 v249, v254, v93
	s_waitcnt lgkmcnt(12)
	global_store_dwordx4 v[236:237], v[238:241], off
	s_nop 0
	ds_bpermute_b32 v238, v254, v72
	ds_bpermute_b32 v239, v254, v73
	ds_bpermute_b32 v240, v254, v74
	ds_bpermute_b32 v241, v254, v75
	ds_bpermute_b32 v236, v254, v76
	ds_bpermute_b32 v237, v254, v77
	s_waitcnt lgkmcnt(12)
	global_store_dwordx4 v[242:243], v[244:247], off
	s_nop 0
	ds_bpermute_b32 v244, v254, v68
	ds_bpermute_b32 v245, v254, v69
	ds_bpermute_b32 v246, v254, v70
	ds_bpermute_b32 v247, v254, v71
	ds_bpermute_b32 v242, v254, v76
	ds_bpermute_b32 v243, v254, v77
	s_waitcnt lgkmcnt(12)
	global_store_dwordx4 v[248:249], v[250:253], off
	s_nop 0
	ds_bpermute_b32 v250, v254, v60
	ds_bpermute_b32 v251, v254, v61
	ds_bpermute_b32 v252, v254, v62
	ds_bpermute_b32 v253, v254, v63
	ds_bpermute_b32 v248, v254, v56
	ds_bpermute_b32 v249, v254, v57
	s_waitcnt lgkmcnt(12)
	global_store_dwordx4 v[236:237], v[238:241], off
	s_nop 0
	ds_bpermute_b32 v238, v254, v40
	ds_bpermute_b32 v239, v254, v41
	ds_bpermute_b32 v240, v254, v42
	ds_bpermute_b32 v241, v254, v43
	ds_bpermute_b32 v236, v254, v46
	ds_bpermute_b32 v237, v254, v47
	s_waitcnt lgkmcnt(12)
	global_store_dwordx4 v[242:243], v[244:247], off offset:256
	s_nop 0
	ds_bpermute_b32 v244, v254, v24
	ds_bpermute_b32 v245, v254, v25
	ds_bpermute_b32 v246, v254, v26
	ds_bpermute_b32 v247, v254, v27
	ds_bpermute_b32 v242, v254, v30
	ds_bpermute_b32 v243, v254, v31
	s_waitcnt lgkmcnt(12)
	global_store_dwordx4 v[248:249], v[250:253], off
	s_nop 0
	ds_bpermute_b32 v250, v254, v8
	ds_bpermute_b32 v251, v254, v9
	ds_bpermute_b32 v252, v254, v10
	ds_bpermute_b32 v253, v254, v11
	ds_bpermute_b32 v248, v254, v14
	ds_bpermute_b32 v249, v254, v15
	s_waitcnt lgkmcnt(12)
	global_store_dwordx4 v[236:237], v[238:241], off
	s_nop 0
	ds_bpermute_b32 v238, v254, v4
	ds_bpermute_b32 v239, v254, v5
	ds_bpermute_b32 v240, v254, v6
	ds_bpermute_b32 v241, v254, v7
	ds_bpermute_b32 v236, v254, v12
	ds_bpermute_b32 v237, v254, v13
	s_waitcnt lgkmcnt(12)
	global_store_dwordx4 v[242:243], v[244:247], off
	s_waitcnt lgkmcnt(6)
	global_store_dwordx4 v[248:249], v[250:253], off
	s_waitcnt lgkmcnt(0)
	global_store_dwordx4 v[236:237], v[238:241], off offset:256
	s_cbranch_vccnz .LBB0_1553
	s_andn2_b64 vcc, exec, s[8:9]
	s_cbranch_vccnz .LBB0_1552
	s_barrier
	s_branch .LBB0_1552

.LBB0_1769:
	v_and_b32_e32 v254, 63, v128
	v_and_b32_e32 v255, 3, v254
	v_lshrrev_b32_e32 v254, 2, v254
	v_lshl_or_b32 v254, v255, 4, v254
	v_lshlrev_b32_e32 v254, 2, v254
	s_cmp_lt_i32 s47, 2
	s_cselect_b32 s22, s54, 0x1aa05000
	s_add_u32 s22, s50, s22
	s_addc_u32 s23, s51, 0
	s_bitcmp1_b32 s47, 0
	s_cselect_b32 s24, 0x2400000, 0
	s_add_u32 s22, s22, s24
	v_lshl_or_b32 v152, s59, 8, v147
	v_lshl_add_u32 v154, s61, 8, v129
	s_addc_u32 s23, s23, 0
	v_ashrrev_i32_e32 v153, 31, v152
	v_ashrrev_i32_e32 v155, 31, v154
	v_lshl_add_u64 v[152:153], v[152:153], 1, s[22:23]
	v_lshlrev_b64 v[156:157], 12, v[154:155]
	v_lshl_add_u64 v[156:157], v[152:153], 0, v[156:157]
	v_cvt_pk_bf16_f32 v60, v60, v61
	v_cvt_pk_bf16_f32 v61, v62, v63
	v_cvt_pk_bf16_f32 v62, v56, v57
	v_add_co_u32_e32 v56, vcc, s55, v156
	v_cvt_pk_bf16_f32 v68, v68, v69
	v_cvt_pk_bf16_f32 v69, v70, v71
	v_cvt_pk_bf16_f32 v70, v64, v65
	v_lshl_add_u64 v[64:65], v[156:157], 0, s[12:13]
	v_addc_co_u32_e32 v57, vcc, 0, v157, vcc
	v_cvt_pk_bf16_f32 v44, v44, v45
	v_cvt_pk_bf16_f32 v45, v46, v47
	v_cvt_pk_bf16_f32 v46, v40, v41
	v_cvt_pk_bf16_f32 v47, v42, v43
	ds_bpermute_b32 v238, v254, v44
	ds_bpermute_b32 v239, v254, v45
	ds_bpermute_b32 v240, v254, v46
	ds_bpermute_b32 v241, v254, v47
	ds_bpermute_b32 v236, v254, v64
	ds_bpermute_b32 v237, v254, v65
	v_cvt_pk_bf16_f32 v108, v108, v109
	v_cvt_pk_bf16_f32 v109, v110, v111
	v_add_co_u32_e32 v46, vcc, s56, v156
	v_cvt_pk_bf16_f32 v110, v104, v105
	v_or_b32_e32 v104, 16, v154
	v_lshl_add_u64 v[44:45], v[156:157], 0, s[14:15]
	v_addc_co_u32_e32 v47, vcc, 0, v157, vcc
	v_cvt_pk_bf16_f32 v28, v28, v29
	v_cvt_pk_bf16_f32 v29, v30, v31
	v_cvt_pk_bf16_f32 v30, v24, v25
	v_cvt_pk_bf16_f32 v31, v26, v27
	v_ashrrev_i32_e32 v105, 31, v104
	v_cvt_pk_bf16_f32 v92, v92, v93
	v_cvt_pk_bf16_f32 v93, v94, v95
	v_cvt_pk_bf16_f32 v94, v88, v89
	v_or_b32_e32 v88, 32, v154
	ds_bpermute_b32 v244, v254, v28
	ds_bpermute_b32 v245, v254, v29
	ds_bpermute_b32 v246, v254, v30
	ds_bpermute_b32 v247, v254, v31
	ds_bpermute_b32 v242, v254, v44
	ds_bpermute_b32 v243, v254, v45
	v_cvt_pk_bf16_f32 v111, v106, v107
	v_lshlrev_b64 v[104:105], 12, v[104:105]
	v_add_co_u32_e32 v30, vcc, s57, v156
	v_ashrrev_i32_e32 v89, 31, v88
	v_cvt_pk_bf16_f32 v76, v76, v77
	v_cvt_pk_bf16_f32 v77, v78, v79
	v_cvt_pk_bf16_f32 v78, v72, v73
	v_or_b32_e32 v72, 48, v154
	v_lshl_add_u64 v[28:29], v[156:157], 0, s[16:17]
	v_addc_co_u32_e32 v31, vcc, 0, v157, vcc
	v_cvt_pk_bf16_f32 v12, v12, v13
	v_cvt_pk_bf16_f32 v13, v14, v15
	v_cvt_pk_bf16_f32 v14, v8, v9
	v_cvt_pk_bf16_f32 v15, v10, v11
	ds_bpermute_b32 v250, v254, v108
	ds_bpermute_b32 v251, v254, v109
	ds_bpermute_b32 v252, v254, v110
	ds_bpermute_b32 v253, v254, v111
	ds_bpermute_b32 v248, v254, v156
	ds_bpermute_b32 v249, v254, v157
	v_cvt_pk_bf16_f32 v95, v90, v91
	v_lshlrev_b64 v[88:89], 12, v[88:89]
	v_lshl_add_u64 v[108:109], v[152:153], 0, v[104:105]
	v_ashrrev_i32_e32 v73, 31, v72
	s_waitcnt lgkmcnt(12)
	global_store_dwordx4 v[236:237], v[238:241], off offset:256
	s_nop 0
	ds_bpermute_b32 v238, v254, v12
	ds_bpermute_b32 v239, v254, v13
	ds_bpermute_b32 v240, v254, v14
	ds_bpermute_b32 v241, v254, v15
	ds_bpermute_b32 v236, v254, v28
	ds_bpermute_b32 v237, v254, v29
	s_waitcnt lgkmcnt(12)
	global_store_dwordx4 v[242:243], v[244:247], off offset:256
	s_nop 0
	ds_bpermute_b32 v244, v254, v92
	ds_bpermute_b32 v245, v254, v93
	ds_bpermute_b32 v246, v254, v94
	ds_bpermute_b32 v247, v254, v95
	ds_bpermute_b32 v242, v254, v108
	ds_bpermute_b32 v243, v254, v109
	v_cvt_pk_bf16_f32 v79, v74, v75
	v_add_co_u32_e32 v14, vcc, s58, v156
	v_lshl_add_u64 v[92:93], v[152:153], 0, v[88:89]
	v_lshlrev_b64 v[72:73], 12, v[72:73]
	v_addc_co_u32_e32 v15, vcc, 0, v157, vcc
	v_cvt_pk_bf16_f32 v124, v124, v125
	v_cvt_pk_bf16_f32 v125, v126, v127
	v_cvt_pk_bf16_f32 v126, v120, v121
	v_cvt_pk_bf16_f32 v127, v122, v123
	v_cvt_pk_bf16_f32 v104, v116, v117
	v_cvt_pk_bf16_f32 v105, v118, v119
	v_cvt_pk_bf16_f32 v106, v112, v113
	v_cvt_pk_bf16_f32 v107, v114, v115
	v_cvt_pk_bf16_f32 v88, v100, v101
	v_cvt_pk_bf16_f32 v89, v102, v103
	v_cvt_pk_bf16_f32 v90, v96, v97
	v_cvt_pk_bf16_f32 v91, v98, v99
	s_waitcnt lgkmcnt(12)
	global_store_dwordx4 v[248:249], v[250:253], off offset:256
	s_nop 0
	ds_bpermute_b32 v250, v254, v76
	ds_bpermute_b32 v251, v254, v77
	ds_bpermute_b32 v252, v254, v78
	ds_bpermute_b32 v253, v254, v79
	ds_bpermute_b32 v248, v254, v92
	ds_bpermute_b32 v249, v254, v93
	v_cvt_pk_bf16_f32 v74, v80, v81
	v_cvt_pk_bf16_f32 v75, v82, v83
	v_lshl_add_u64 v[76:77], v[152:153], 0, v[72:73]
	v_cvt_pk_bf16_f32 v72, v84, v85
	v_cvt_pk_bf16_f32 v73, v86, v87
	v_cvt_pk_bf16_f32 v71, v66, v67
	v_cvt_pk_bf16_f32 v63, v58, v59
	v_cvt_pk_bf16_f32 v40, v52, v53
	v_cvt_pk_bf16_f32 v41, v54, v55
	v_cvt_pk_bf16_f32 v42, v48, v49
	v_cvt_pk_bf16_f32 v43, v50, v51
	v_cvt_pk_bf16_f32 v24, v36, v37
	v_cvt_pk_bf16_f32 v25, v38, v39
	v_cvt_pk_bf16_f32 v26, v32, v33
	v_cvt_pk_bf16_f32 v27, v34, v35
	v_lshl_add_u64 v[12:13], v[156:157], 0, s[18:19]
	v_cvt_pk_bf16_f32 v8, v20, v21
	v_cvt_pk_bf16_f32 v9, v22, v23
	v_cvt_pk_bf16_f32 v10, v16, v17
	v_cvt_pk_bf16_f32 v11, v18, v19
	v_cvt_pk_bf16_f32 v4, v4, v5
	v_cvt_pk_bf16_f32 v5, v6, v7
	v_cvt_pk_bf16_f32 v6, v0, v1
	v_cvt_pk_bf16_f32 v7, v2, v3
	s_and_b64 vcc, exec, s[4:5]
	s_mov_b64 s[4:5], -1
	s_waitcnt lgkmcnt(12)
	global_store_dwordx4 v[236:237], v[238:241], off offset:256
	s_nop 0
	ds_bpermute_b32 v238, v254, v124
	ds_bpermute_b32 v239, v254, v125
	ds_bpermute_b32 v240, v254, v126
	ds_bpermute_b32 v241, v254, v127
	ds_bpermute_b32 v236, v254, v156
	ds_bpermute_b32 v237, v254, v157
	s_waitcnt lgkmcnt(12)
	global_store_dwordx4 v[242:243], v[244:247], off offset:256
	s_nop 0
	ds_bpermute_b32 v244, v254, v104
	ds_bpermute_b32 v245, v254, v105
	ds_bpermute_b32 v246, v254, v106
	ds_bpermute_b32 v247, v254, v107
	ds_bpermute_b32 v242, v254, v108
	ds_bpermute_b32 v243, v254, v109
	s_waitcnt lgkmcnt(12)
	global_store_dwordx4 v[248:249], v[250:253], off offset:256
	s_nop 0
	ds_bpermute_b32 v250, v254, v88
	ds_bpermute_b32 v251, v254, v89
	ds_bpermute_b32 v252, v254, v90
	ds_bpermute_b32 v253, v254, v91
	ds_bpermute_b32 v248, v254, v92
	ds_bpermute_b32 v249, v254, v93
	s_waitcnt lgkmcnt(12)
	global_store_dwordx4 v[236:237], v[238:241], off
	s_nop 0
	ds_bpermute_b32 v238, v254, v72
	ds_bpermute_b32 v239, v254, v73
	ds_bpermute_b32 v240, v254, v74
	ds_bpermute_b32 v241, v254, v75
	ds_bpermute_b32 v236, v254, v76
	ds_bpermute_b32 v237, v254, v77
	s_waitcnt lgkmcnt(12)
	global_store_dwordx4 v[242:243], v[244:247], off
	s_nop 0
	ds_bpermute_b32 v244, v254, v68
	ds_bpermute_b32 v245, v254, v69
	ds_bpermute_b32 v246, v254, v70
	ds_bpermute_b32 v247, v254, v71
	ds_bpermute_b32 v242, v254, v76
	ds_bpermute_b32 v243, v254, v77
	s_waitcnt lgkmcnt(12)
	global_store_dwordx4 v[248:249], v[250:253], off
	s_nop 0
	ds_bpermute_b32 v250, v254, v60
	ds_bpermute_b32 v251, v254, v61
	ds_bpermute_b32 v252, v254, v62
	ds_bpermute_b32 v253, v254, v63
	ds_bpermute_b32 v248, v254, v56
	ds_bpermute_b32 v249, v254, v57
	s_waitcnt lgkmcnt(12)
	global_store_dwordx4 v[236:237], v[238:241], off
	s_nop 0
	ds_bpermute_b32 v238, v254, v40
	ds_bpermute_b32 v239, v254, v41
	ds_bpermute_b32 v240, v254, v42
	ds_bpermute_b32 v241, v254, v43
	ds_bpermute_b32 v236, v254, v46
	ds_bpermute_b32 v237, v254, v47
	s_waitcnt lgkmcnt(12)
	global_store_dwordx4 v[242:243], v[244:247], off offset:256
	s_nop 0
	ds_bpermute_b32 v244, v254, v24
	ds_bpermute_b32 v245, v254, v25
	ds_bpermute_b32 v246, v254, v26
	ds_bpermute_b32 v247, v254, v27
	ds_bpermute_b32 v242, v254, v30
	ds_bpermute_b32 v243, v254, v31
	s_waitcnt lgkmcnt(12)
	global_store_dwordx4 v[248:249], v[250:253], off
	s_nop 0
	ds_bpermute_b32 v250, v254, v8
	ds_bpermute_b32 v251, v254, v9
	ds_bpermute_b32 v252, v254, v10
	ds_bpermute_b32 v253, v254, v11
	ds_bpermute_b32 v248, v254, v14
	ds_bpermute_b32 v249, v254, v15
	s_waitcnt lgkmcnt(12)
	global_store_dwordx4 v[236:237], v[238:241], off
	s_nop 0
	ds_bpermute_b32 v238, v254, v4
	ds_bpermute_b32 v239, v254, v5
	ds_bpermute_b32 v240, v254, v6
	ds_bpermute_b32 v241, v254, v7
	ds_bpermute_b32 v236, v254, v12
	ds_bpermute_b32 v237, v254, v13
	s_waitcnt lgkmcnt(12)
	global_store_dwordx4 v[242:243], v[244:247], off
	s_waitcnt lgkmcnt(6)
	global_store_dwordx4 v[248:249], v[250:253], off
	s_waitcnt lgkmcnt(0)
	global_store_dwordx4 v[236:237], v[238:241], off offset:256
	s_cbranch_vccnz .LBB0_1758
	s_andn2_b64 vcc, exec, s[0:1]
	s_cbranch_vccnz .LBB0_1757
	s_barrier
	s_branch .LBB0_1757
